# MLA_IN seam: weight transposes spread over all blocks as 1024 virtual workers (lower-half blocks 1, upper-half blocks 3) instead of upper half only
# baseline (speedup 1.0000x reference)
; DI int opaque_tid() { int t = threadIdx.x; asm volatile("" : "+v"(t)); return t; }
; DI void transpose_job(const float* __restrict__ src, int K, int N, int Npad, bf16* __restrict__ dst, const float* __restrict__ gain, float* tile, int bid, int nb) {
;   const int tid = opaque_tid();
;   const int kt_n = K / 64, nt_n = Npad / 64;
;   for (int t = bid; t < kt_n * nt_n; t += nb) {
;     const int kt = t % kt_n, nt = t / kt_n;
;     __syncthreads();
; #pragma unroll
;     for (int i = 0; i < 4; ++i) {
;       int k = (tid >> 4) + 16 * i;
;       int n = nt * 64 + (tid & 15) * 4;
;       float4 v = make_float4(0.f, 0.f, 0.f, 0.f);
;       if (n < N) v = *(const float4*)(src + (size_t)(kt * 64 + k) * N + n);
;       float gn = gain ? gain[kt * 64 + k] : 1.f;
;       float* tp = tile + k * 65 + (tid & 15) * 4;
; __global__ void __launch_bounds__(256, 2) fwd_megakernel(Params p) {
;     ...
;   {
;     const int half = (int)(gridDim.x >> 1);
;     if (half > 0 && (int)blockIdx.x >= half) prep_deferred(p, smem, (int)blockIdx.x - half, (int)gridDim.x - half);
;     else if (half == 0) prep_deferred(p, smem, 0, 1);
;   }
.LBB0_99:
	s_or_b64 exec, exec, s[6:7]
	s_lshr_b32 s33, s26, 1
	s_cmp_lt_u32 s26, 2
	v_readlane_b32 s4, v255, 0
	s_cselect_b64 s[10:11], -1, 0
	s_cmp_lt_i32 s4, s33
	s_cselect_b64 s[0:1], -1, 0
	s_or_b64 s[0:1], s[10:11], s[0:1]
	s_and_b64 vcc, exec, s[0:1]
	s_waitcnt lgkmcnt(0)
	s_barrier
	v_readlane_b32 s5, v255, 1
	s_cmp_lg_u32 s26, 0x200
	s_cbranch_scc1 .Lmy_pd_orig
	s_mov_b32 s100, 0
	s_movk_i32 s5, 0x400
	s_cmp_lt_i32 s4, s33
	s_cbranch_scc1 .Lmy_pd_lower
	s_sub_i32 s99, s4, s33
	s_mul_i32 s99, s99, 3
	s_add_i32 s99, s99, 0x100
	s_mov_b32 s98, 3
	s_branch .Lmy_pd_entry0
.Lmy_pd_lower:
	s_mov_b32 s99, s4
	s_mov_b32 s98, 1
	s_mov_b32 s100, 1
.Lmy_pd_entry0:
	s_mov_b32 s4, s99
	s_branch .Lmy_pd_entry
.Lmy_pd_orig:
	s_cbranch_vccnz .LBB0_124
	s_sub_i32 s4, s4, s33
	s_sub_i32 s5, s26, s33
.Lmy_pd_entry:
	v_mov_b32_e32 v0, v160
	s_cmpk_gt_i32 s4, 0x8f
	s_cbranch_scc1 .LBB0_125
	s_load_dwordx2 s[12:13], s[2:3], 0x10
	s_load_dwordx2 s[14:15], s[2:3], 0x20
	v_ashrrev_i32_e32 v4, 4, v0
	v_lshlrev_b32_e32 v1, 2, v0
	v_ashrrev_i32_e32 v12, 3, v0
	v_lshlrev_b32_e32 v0, 3, v0
	v_and_b32_e32 v3, 56, v0
	v_and_b32_e32 v11, 60, v1
	v_lshlrev_b32_e32 v0, 1, v3
	v_mov_b32_e32 v1, 0
	v_lshl_add_u64 v[0:1], s[22:23], 0, v[0:1]
	s_mov_b64 s[0:1], 0x19c80000
	s_waitcnt lgkmcnt(0)
	s_cmp_lg_u64 s[12:13], 0
	v_lshl_add_u64 v[6:7], v[0:1], 0, s[0:1]
	s_movk_i32 s0, 0x104
	s_cselect_b64 s[16:17], -1, 0
	v_lshlrev_b32_e32 v2, 2, v11
	v_lshlrev_b32_e32 v0, 2, v12
	v_mul_u32_u24_e32 v1, 0x104, v3
	v_mul_lo_u32 v3, v4, s0
	v_cndmask_b32_e64 v8, 0, 1, s[16:17]
	v_add_u32_e32 v13, v2, v3
	v_add_u32_e32 v20, v0, v1
	v_ashrrev_i32_e32 v5, 31, v4
	s_lshl_b32 s0, s4, 6
	s_lshl_b32 s1, s5, 6
	s_movk_i32 s28, 0x600
	s_movk_i32 s29, 0x1800
	v_cmp_ne_u32_e64 s[6:7], 1, v8
	v_add_u32_e32 v14, 0x1040, v13
	v_add_u32_e32 v15, 0x1048, v13
	v_add_u32_e32 v16, 0x2080, v13
	v_add_u32_e32 v17, 0x2088, v13
	v_add_u32_e32 v18, 0x30c0, v13
	v_add_u32_e32 v19, 0x30c8, v13
	s_movk_i32 s30, 0x300
	v_add_u32_e32 v21, 0x400, v20
	s_mov_b32 s31, s4
	s_branch .LBB0_103

; DI void prep_deferred(const Params& p, unsigned char* smem, int bid, int nb) {
;   unsigned char* ws = p.ws;
;   float* tile = (float*)smem;
;   transpose_job(p.mla_w_uq, 384, 1536, 1536, (bf16*)(ws + OFF_WUQ_T), p.mla_q_norm, tile, bid, nb);
;   transpose_job(p.mla_w_ukv, 256, 2048, 2048, (bf16*)(ws + OFF_WUKV_T), p.mla_kv_norm, tile, bid, nb);
;   transpose_job(p.mla_w_o, 1024, 1024, 1024, (bf16*)(ws + OFF_WO_T), nullptr, tile, bid, nb);
;   transpose_job(p.dsa_w_in, 1024, 3656, 3712, (bf16*)(ws + OFF_DIN_T), nullptr, tile, bid, nb);
;   transpose_job(p.dsa_w_o, 1024, 1024, 1024, (bf16*)(ws + OFF_DO_T), nullptr, tile, bid, nb);
;   transpose_job(p.peer_w_q, 1024, 2048, 2048, (bf16*)(ws + OFF_WQ_T), nullptr, tile, bid, nb);
;   transpose_job(p.peer_w_q + (size_t)1024 * 2048, 1024, 2048, 2048, (bf16*)(ws + OFF_WQ_T) + (size_t)2048 * 1024, nullptr, tile, bid, nb);
;   __syncthreads();
; }
; __global__ void __launch_bounds__(256, 2) fwd_megakernel(Params p) {
;     ...
;   {
;     const int half = (int)(gridDim.x >> 1);
;     if (half > 0 && (int)blockIdx.x >= half) prep_deferred(p, smem, (int)blockIdx.x - half, (int)gridDim.x - half);
;     else if (half == 0) prep_deferred(p, smem, 0, 1);
;   }
.LBB0_174:
	s_waitcnt lgkmcnt(0)
	s_barrier
	s_cmp_lg_u32 s26, 0x200
	s_cbranch_scc1 .Lmy_pd_fin
	s_sub_u32 s98, s98, 1
	s_cmp_eq_u32 s98, 0
	s_cbranch_scc1 .Lmy_pd_last
	s_add_i32 s99, s99, 1
	s_mov_b32 s4, s99
	s_branch .Lmy_pd_entry
.Lmy_pd_last:
	s_cmp_eq_u32 s100, 1
	s_cbranch_scc0 .Lmy_pd_fin
	s_mov_b64 s[6:7], 0
	s_branch .LBB0_221
.Lmy_pd_fin:
	s_mov_b64 s[6:7], -1
	s_branch .LBB0_221
